# DA: running-sum adds moved into the exp gaps so the VALU work is level across all 12 MFMA gaps of a step
# speedup vs baseline: 1.0348x; 1.0032x over previous
.LBB0_164:
	s_add_i32 s8, s8, 0
	v_add_u32_e32 v80, s8, v188
	v_xor_b32_e32 v84, 0x60, v80
	v_xor_b32_e32 v92, 32, v80
	ds_read_b128 v[80:83], v84
	ds_read_b128 v[84:87], v84 offset:8192
	ds_read_b128 v[88:91], v92 offset:4096
	ds_read_b128 v[92:95], v92 offset:12288
	s_waitcnt lgkmcnt(8)
	v_mfma_f32_32x32x16_bf16 v[48:63], v[140:143], v[148:151], v[48:63]
	v_exp_f32_e32 v156, v64
	v_exp_f32_e32 v157, v65
	s_waitcnt lgkmcnt(6)
	v_mfma_f32_32x32x16_bf16 v[32:47], v[136:139], v[148:151], v[32:47]
	v_exp_f32_e32 v158, v66
	v_exp_f32_e32 v159, v67
	v_add_f32_e32 v253, v157, v156
	v_mfma_f32_32x32x16_bf16 v[16:31], v[132:135], v[148:151], v[16:31]
	v_exp_f32_e32 v160, v68
	v_exp_f32_e32 v161, v69
	v_add_f32_e32 v253, v158, v253
	v_add_f32_e32 v253, v159, v253
	s_waitcnt lgkmcnt(5)
	v_mfma_f32_32x32x16_bf16 v[0:15], v[128:131], v[148:151], v[0:15]
	s_add_i32 s87, s82, 0
	s_add_i32 s8, s36, s87
	v_add3_u32 v128, s8, v186, v174
	ds_read_b128 v[148:151], v128 offset:8704
	ds_read_b128 v[192:195], v128 offset:8736
	ds_read_b128 v[198:201], v128 offset:8768
	ds_read_b128 v[224:227], v128 offset:8800
	v_exp_f32_e32 v162, v70
	v_exp_f32_e32 v163, v71
	v_add_f32_e32 v253, v160, v253
	v_add_f32_e32 v253, v161, v253
	s_waitcnt lgkmcnt(7)
	v_mfma_f32_32x32x16_bf16 v[48:63], v[80:83], v[144:147], v[48:63]
	v_add_u32_e32 v190, s87, v188
	v_xor_b32_e32 v191, 64, v190
	ds_read_b128 v[128:131], v190
	ds_read_b128 v[132:135], v191 offset:4096
	ds_read_b128 v[136:139], v190 offset:8192
	ds_read_b128 v[140:143], v191 offset:12288
	v_exp_f32_e32 v214, v72
	v_exp_f32_e32 v215, v73
	v_add_f32_e32 v253, v162, v253
	v_add_f32_e32 v253, v163, v253
	s_waitcnt lgkmcnt(9)
	v_mfma_f32_32x32x16_bf16 v[32:47], v[88:91], v[144:147], v[32:47]
	v_exp_f32_e32 v216, v74
	v_exp_f32_e32 v217, v75
	v_add_f32_e32 v253, v214, v253
	v_add_f32_e32 v253, v215, v253
	v_mfma_f32_32x32x16_bf16 v[16:31], v[84:87], v[144:147], v[16:31]
	v_exp_f32_e32 v218, v76
	v_exp_f32_e32 v219, v77
	v_add_f32_e32 v253, v216, v253
	v_add_f32_e32 v253, v217, v253
	s_waitcnt lgkmcnt(8)
	v_mfma_f32_32x32x16_bf16 v[0:15], v[92:95], v[144:147], v[0:15]
	v_exp_f32_e32 v220, v78
	v_exp_f32_e32 v221, v79
	v_add_f32_e32 v253, v218, v253
	v_add_f32_e32 v253, v219, v253
	s_waitcnt lgkmcnt(7)
	v_mfma_f32_32x32x16_bf16 v[80:95], v[148:151], v[104:107], v[232:247]
	v_add_f32_e32 v253, v220, v253
	v_cvt_pk_bf16_f32 v144, v156, v157
	v_cvt_pk_bf16_f32 v145, v158, v159
	s_waitcnt lgkmcnt(6)
	v_mfma_f32_32x32x16_bf16 v[80:95], v[192:195], v[96:99], v[80:95]
	v_cvt_pk_bf16_f32 v146, v160, v161
	v_cvt_pk_bf16_f32 v147, v162, v163
	s_waitcnt lgkmcnt(5)
	v_mfma_f32_32x32x16_bf16 v[80:95], v[198:201], v[100:103], v[80:95]
	v_cvt_pk_bf16_f32 v148, v214, v215
	v_cvt_pk_bf16_f32 v149, v216, v217
	s_waitcnt lgkmcnt(4)
	v_mfma_f32_32x32x16_bf16 v[80:95], v[224:227], v[108:111], v[80:95]
	v_add_f32_e32 v192, v221, v253
	v_cvt_pk_bf16_f32 v150, v218, v219
	v_cvt_pk_bf16_f32 v151, v220, v221
	v_cmp_ngt_f32_e32 vcc, s68, v192
	s_cbranch_vccz .LBB0_167
	v_max3_f32 v250, v64, v65, v66
	v_max3_f32 v251, v67, v68, v69
	v_max3_f32 v250, v250, v70, v71
	v_max3_f32 v251, v251, v72, v73
	v_max3_f32 v250, v250, v74, v75
	v_max3_f32 v251, v251, v76, v77
	v_max3_f32 v250, v250, v78, v79
	v_max_f32_e32 v250, v250, v251
	v_mov_b32_e32 v251, v250
	s_nop 1
	v_permlane32_swap_b32_e32 v250, v251
	v_max_f32_e32 v250, v250, v251
	v_cmp_lt_f32_e32 vcc, v154, v250
	s_cbranch_vccz .LBB0_167
	s_nop 1
	v_cndmask_b32_e32 v250, 0, v250, vcc
	v_sub_f32_e32 v251, 0, v250
	v_exp_f32_e32 v251, v251
	s_nop 0
	v_mul_f32_e32 v0, v251, v0
	v_mul_f32_e32 v1, v251, v1
	v_mul_f32_e32 v2, v251, v2
	v_mul_f32_e32 v3, v251, v3
	v_mul_f32_e32 v4, v251, v4
	v_mul_f32_e32 v5, v251, v5
	v_mul_f32_e32 v6, v251, v6
	v_mul_f32_e32 v7, v251, v7
	v_mul_f32_e32 v8, v251, v8
	v_mul_f32_e32 v9, v251, v9
	v_mul_f32_e32 v10, v251, v10
	v_mul_f32_e32 v11, v251, v11
	v_mul_f32_e32 v12, v251, v12
	v_mul_f32_e32 v13, v251, v13
	v_mul_f32_e32 v14, v251, v14
	v_mul_f32_e32 v15, v251, v15
	v_mul_f32_e32 v16, v251, v16
	v_mul_f32_e32 v17, v251, v17
	v_mul_f32_e32 v18, v251, v18
	v_mul_f32_e32 v19, v251, v19
	v_mul_f32_e32 v20, v251, v20
	v_mul_f32_e32 v21, v251, v21
	v_mul_f32_e32 v22, v251, v22
	v_mul_f32_e32 v23, v251, v23
	v_mul_f32_e32 v24, v251, v24
	v_mul_f32_e32 v25, v251, v25
	v_mul_f32_e32 v26, v251, v26
	v_mul_f32_e32 v27, v251, v27
	v_mul_f32_e32 v28, v251, v28
	v_mul_f32_e32 v29, v251, v29
	v_mul_f32_e32 v30, v251, v30
	v_mul_f32_e32 v31, v251, v31
	v_mul_f32_e32 v32, v251, v32
	v_mul_f32_e32 v33, v251, v33
	v_mul_f32_e32 v34, v251, v34
	v_mul_f32_e32 v35, v251, v35
	v_mul_f32_e32 v36, v251, v36
	v_mul_f32_e32 v37, v251, v37
	v_mul_f32_e32 v38, v251, v38
	v_mul_f32_e32 v39, v251, v39
	v_mul_f32_e32 v40, v251, v40
	v_mul_f32_e32 v41, v251, v41
	v_mul_f32_e32 v42, v251, v42
	v_mul_f32_e32 v43, v251, v43
	v_mul_f32_e32 v44, v251, v44
	v_mul_f32_e32 v45, v251, v45
	v_mul_f32_e32 v46, v251, v46
	v_mul_f32_e32 v47, v251, v47
	v_mul_f32_e32 v48, v251, v48
	v_mul_f32_e32 v49, v251, v49
	v_mul_f32_e32 v50, v251, v50
	v_mul_f32_e32 v51, v251, v51
	v_mul_f32_e32 v52, v251, v52
	v_mul_f32_e32 v53, v251, v53
	v_mul_f32_e32 v54, v251, v54
	v_mul_f32_e32 v55, v251, v55
	v_mul_f32_e32 v56, v251, v56
	v_mul_f32_e32 v57, v251, v57
	v_mul_f32_e32 v58, v251, v58
	v_mul_f32_e32 v59, v251, v59
	v_mul_f32_e32 v60, v251, v60
	v_mul_f32_e32 v61, v251, v61
	v_mul_f32_e32 v62, v251, v62
	v_mul_f32_e32 v63, v251, v63
	v_mul_f32_e32 v178, v251, v178
	v_sub_f32_e32 v64, v64, v250
	v_sub_f32_e32 v65, v65, v250
	v_sub_f32_e32 v66, v66, v250
	v_sub_f32_e32 v67, v67, v250
	v_sub_f32_e32 v68, v68, v250
	v_sub_f32_e32 v69, v69, v250
	v_sub_f32_e32 v70, v70, v250
	v_sub_f32_e32 v71, v71, v250
	v_sub_f32_e32 v72, v72, v250
	v_sub_f32_e32 v73, v73, v250
	v_sub_f32_e32 v74, v74, v250
	v_sub_f32_e32 v75, v75, v250
	v_sub_f32_e32 v76, v76, v250
	v_sub_f32_e32 v77, v77, v250
	v_sub_f32_e32 v78, v78, v250
	v_sub_f32_e32 v79, v79, v250
	v_sub_f32_e32 v80, v80, v250
	v_sub_f32_e32 v81, v81, v250
	v_sub_f32_e32 v82, v82, v250
	v_sub_f32_e32 v83, v83, v250
	v_sub_f32_e32 v84, v84, v250
	v_sub_f32_e32 v85, v85, v250
	v_sub_f32_e32 v86, v86, v250
	v_sub_f32_e32 v87, v87, v250
	v_sub_f32_e32 v88, v88, v250
	v_sub_f32_e32 v89, v89, v250
	v_sub_f32_e32 v90, v90, v250
	v_sub_f32_e32 v91, v91, v250
	v_sub_f32_e32 v92, v92, v250
	v_sub_f32_e32 v93, v93, v250
	v_sub_f32_e32 v94, v94, v250
	v_sub_f32_e32 v95, v95, v250
	v_sub_f32_e32 v232, v232, v250
	v_sub_f32_e32 v233, v233, v250
	v_sub_f32_e32 v234, v234, v250
	v_sub_f32_e32 v235, v235, v250
	v_sub_f32_e32 v236, v236, v250
	v_sub_f32_e32 v237, v237, v250
	v_sub_f32_e32 v238, v238, v250
	v_sub_f32_e32 v239, v239, v250
	v_sub_f32_e32 v240, v240, v250
	v_sub_f32_e32 v241, v241, v250
	v_sub_f32_e32 v242, v242, v250
	v_sub_f32_e32 v243, v243, v250
	v_sub_f32_e32 v244, v244, v250
	v_sub_f32_e32 v245, v245, v250
	v_sub_f32_e32 v246, v246, v250
	v_sub_f32_e32 v247, v247, v250
	v_exp_f32_e32 v156, v64
	v_exp_f32_e32 v157, v65
	v_exp_f32_e32 v158, v66
	v_exp_f32_e32 v159, v67
	v_exp_f32_e32 v160, v68
	v_exp_f32_e32 v161, v69
	v_exp_f32_e32 v162, v70
	v_exp_f32_e32 v163, v71
	v_exp_f32_e32 v214, v72
	v_exp_f32_e32 v215, v73
	v_exp_f32_e32 v216, v74
	v_exp_f32_e32 v217, v75
	v_exp_f32_e32 v218, v76
	v_exp_f32_e32 v219, v77
	v_exp_f32_e32 v220, v78
	v_exp_f32_e32 v221, v79
	s_nop 0
	v_add_f32_e32 v253, v157, v156
	v_add_f32_e32 v253, v158, v253
	v_add_f32_e32 v253, v159, v253
	v_add_f32_e32 v253, v160, v253
	v_add_f32_e32 v253, v161, v253
	v_add_f32_e32 v253, v162, v253
	v_add_f32_e32 v253, v163, v253
	v_add_f32_e32 v253, v214, v253
	v_add_f32_e32 v253, v215, v253
	v_add_f32_e32 v253, v216, v253
	v_add_f32_e32 v253, v217, v253
	v_add_f32_e32 v253, v218, v253
	v_add_f32_e32 v253, v219, v253
	v_add_f32_e32 v253, v220, v253
	v_add_f32_e32 v192, v221, v253
	v_cvt_pk_bf16_f32 v144, v156, v157
	v_cvt_pk_bf16_f32 v145, v158, v159
	v_cvt_pk_bf16_f32 v146, v160, v161
	v_cvt_pk_bf16_f32 v147, v162, v163
	v_cvt_pk_bf16_f32 v148, v214, v215
	v_cvt_pk_bf16_f32 v149, v216, v217
	v_cvt_pk_bf16_f32 v150, v218, v219
	v_cvt_pk_bf16_f32 v151, v220, v221

.LBB0_169:
	v_add_f32_e32 v192, v192, v178
	v_xor_b32_e32 v155, 32, v190
	v_xor_b32_e32 v178, 0x60, v190
	ds_read_b128 v[64:67], v155
	ds_read_b128 v[68:71], v178 offset:4096
	ds_read_b128 v[72:75], v155 offset:8192
	ds_read_b128 v[76:79], v178 offset:12288
	v_mfma_f32_32x32x16_bf16 v[48:63], v[128:131], v[144:147], v[48:63]
	v_exp_f32_e32 v156, v80
	v_exp_f32_e32 v157, v81
	v_mfma_f32_32x32x16_bf16 v[32:47], v[132:135], v[144:147], v[32:47]
	v_exp_f32_e32 v158, v82
	v_exp_f32_e32 v159, v83
	v_add_f32_e32 v253, v157, v156
	v_mfma_f32_32x32x16_bf16 v[16:31], v[136:139], v[144:147], v[16:31]
	v_exp_f32_e32 v160, v84
	v_exp_f32_e32 v161, v85
	v_add_f32_e32 v253, v158, v253
	v_add_f32_e32 v253, v159, v253
	v_mfma_f32_32x32x16_bf16 v[0:15], v[140:143], v[144:147], v[0:15]
	v_add_u32_e32 v128, s84, v187
	ds_read_b128 v[144:147], v128
	ds_read_b128 v[198:201], v128 offset:32
	ds_read_b128 v[224:227], v128 offset:64
	ds_read_b128 v[228:231], v128 offset:96
	v_exp_f32_e32 v162, v86
	v_exp_f32_e32 v163, v87
	v_add_f32_e32 v253, v160, v253
	v_add_f32_e32 v253, v161, v253
	s_waitcnt lgkmcnt(7)
	v_mfma_f32_32x32x16_bf16 v[48:63], v[64:67], v[148:151], v[48:63]
	ds_read_b128 v[132:135], v191
	ds_read_b128 v[128:131], v190 offset:4096
	ds_read_b128 v[136:139], v191 offset:8192
	ds_read_b128 v[140:143], v190 offset:12288
	v_exp_f32_e32 v214, v88
	v_exp_f32_e32 v215, v89
	v_add_f32_e32 v253, v162, v253
	v_add_f32_e32 v253, v163, v253
	s_waitcnt lgkmcnt(10)
	v_mfma_f32_32x32x16_bf16 v[32:47], v[68:71], v[148:151], v[32:47]
	v_exp_f32_e32 v216, v90
	v_exp_f32_e32 v217, v91
	v_add_f32_e32 v253, v214, v253
	v_add_f32_e32 v253, v215, v253
	s_waitcnt lgkmcnt(9)
	v_mfma_f32_32x32x16_bf16 v[16:31], v[72:75], v[148:151], v[16:31]
	v_exp_f32_e32 v218, v92
	v_exp_f32_e32 v219, v93
	v_add_f32_e32 v253, v216, v253
	v_add_f32_e32 v253, v217, v253
	s_waitcnt lgkmcnt(8)
	v_mfma_f32_32x32x16_bf16 v[0:15], v[76:79], v[148:151], v[0:15]
	v_exp_f32_e32 v220, v94
	v_exp_f32_e32 v221, v95
	v_add_f32_e32 v253, v218, v253
	v_add_f32_e32 v253, v219, v253
	s_waitcnt lgkmcnt(7)
	v_mfma_f32_32x32x16_bf16 v[64:79], v[144:147], v[104:107], v[232:247]
	v_add_f32_e32 v253, v220, v253
	v_cvt_pk_bf16_f32 v148, v214, v215
	v_cvt_pk_bf16_f32 v149, v216, v217
	s_waitcnt lgkmcnt(6)
	v_mfma_f32_32x32x16_bf16 v[64:79], v[198:201], v[96:99], v[64:79]
	v_cvt_pk_bf16_f32 v150, v218, v219
	v_cvt_pk_bf16_f32 v151, v220, v221
	s_waitcnt lgkmcnt(5)
	v_mfma_f32_32x32x16_bf16 v[64:79], v[224:227], v[100:103], v[64:79]
	v_cvt_pk_bf16_f32 v144, v156, v157
	v_cvt_pk_bf16_f32 v145, v158, v159
	s_waitcnt lgkmcnt(4)
	v_mfma_f32_32x32x16_bf16 v[64:79], v[228:231], v[108:111], v[64:79]
	v_add_f32_e32 v190, v221, v253
	v_cvt_pk_bf16_f32 v146, v160, v161
	v_cvt_pk_bf16_f32 v147, v162, v163
	v_cmp_ngt_f32_e32 vcc, s68, v190
	s_cbranch_vccz .LBB0_172
	v_max3_f32 v250, v80, v81, v82
	v_max3_f32 v251, v83, v84, v85
	v_max3_f32 v250, v250, v86, v87
	v_max3_f32 v251, v251, v88, v89
	v_max3_f32 v250, v250, v90, v91
	v_max3_f32 v251, v251, v92, v93
	v_max3_f32 v250, v250, v94, v95
	v_max_f32_e32 v250, v250, v251
	v_mov_b32_e32 v251, v250
	s_nop 1
	v_permlane32_swap_b32_e32 v250, v251
	v_max_f32_e32 v250, v250, v251
	v_cmp_lt_f32_e32 vcc, v154, v250
	s_cbranch_vccz .LBB0_172
	s_nop 1
	v_cndmask_b32_e32 v250, 0, v250, vcc
	v_sub_f32_e32 v251, 0, v250
	v_exp_f32_e32 v251, v251
	s_nop 0
	v_mul_f32_e32 v0, v251, v0
	v_mul_f32_e32 v1, v251, v1
	v_mul_f32_e32 v2, v251, v2
	v_mul_f32_e32 v3, v251, v3
	v_mul_f32_e32 v4, v251, v4
	v_mul_f32_e32 v5, v251, v5
	v_mul_f32_e32 v6, v251, v6
	v_mul_f32_e32 v7, v251, v7
	v_mul_f32_e32 v8, v251, v8
	v_mul_f32_e32 v9, v251, v9
	v_mul_f32_e32 v10, v251, v10
	v_mul_f32_e32 v11, v251, v11
	v_mul_f32_e32 v12, v251, v12
	v_mul_f32_e32 v13, v251, v13
	v_mul_f32_e32 v14, v251, v14
	v_mul_f32_e32 v15, v251, v15
	v_mul_f32_e32 v16, v251, v16
	v_mul_f32_e32 v17, v251, v17
	v_mul_f32_e32 v18, v251, v18
	v_mul_f32_e32 v19, v251, v19
	v_mul_f32_e32 v20, v251, v20
	v_mul_f32_e32 v21, v251, v21
	v_mul_f32_e32 v22, v251, v22
	v_mul_f32_e32 v23, v251, v23
	v_mul_f32_e32 v24, v251, v24
	v_mul_f32_e32 v25, v251, v25
	v_mul_f32_e32 v26, v251, v26
	v_mul_f32_e32 v27, v251, v27
	v_mul_f32_e32 v28, v251, v28
	v_mul_f32_e32 v29, v251, v29
	v_mul_f32_e32 v30, v251, v30
	v_mul_f32_e32 v31, v251, v31
	v_mul_f32_e32 v32, v251, v32
	v_mul_f32_e32 v33, v251, v33
	v_mul_f32_e32 v34, v251, v34
	v_mul_f32_e32 v35, v251, v35
	v_mul_f32_e32 v36, v251, v36
	v_mul_f32_e32 v37, v251, v37
	v_mul_f32_e32 v38, v251, v38
	v_mul_f32_e32 v39, v251, v39
	v_mul_f32_e32 v40, v251, v40
	v_mul_f32_e32 v41, v251, v41
	v_mul_f32_e32 v42, v251, v42
	v_mul_f32_e32 v43, v251, v43
	v_mul_f32_e32 v44, v251, v44
	v_mul_f32_e32 v45, v251, v45
	v_mul_f32_e32 v46, v251, v46
	v_mul_f32_e32 v47, v251, v47
	v_mul_f32_e32 v48, v251, v48
	v_mul_f32_e32 v49, v251, v49
	v_mul_f32_e32 v50, v251, v50
	v_mul_f32_e32 v51, v251, v51
	v_mul_f32_e32 v52, v251, v52
	v_mul_f32_e32 v53, v251, v53
	v_mul_f32_e32 v54, v251, v54
	v_mul_f32_e32 v55, v251, v55
	v_mul_f32_e32 v56, v251, v56
	v_mul_f32_e32 v57, v251, v57
	v_mul_f32_e32 v58, v251, v58
	v_mul_f32_e32 v59, v251, v59
	v_mul_f32_e32 v60, v251, v60
	v_mul_f32_e32 v61, v251, v61
	v_mul_f32_e32 v62, v251, v62
	v_mul_f32_e32 v63, v251, v63
	v_mul_f32_e32 v192, v251, v192
	v_sub_f32_e32 v80, v80, v250
	v_sub_f32_e32 v81, v81, v250
	v_sub_f32_e32 v82, v82, v250
	v_sub_f32_e32 v83, v83, v250
	v_sub_f32_e32 v84, v84, v250
	v_sub_f32_e32 v85, v85, v250
	v_sub_f32_e32 v86, v86, v250
	v_sub_f32_e32 v87, v87, v250
	v_sub_f32_e32 v88, v88, v250
	v_sub_f32_e32 v89, v89, v250
	v_sub_f32_e32 v90, v90, v250
	v_sub_f32_e32 v91, v91, v250
	v_sub_f32_e32 v92, v92, v250
	v_sub_f32_e32 v93, v93, v250
	v_sub_f32_e32 v94, v94, v250
	v_sub_f32_e32 v95, v95, v250
	v_sub_f32_e32 v64, v64, v250
	v_sub_f32_e32 v65, v65, v250
	v_sub_f32_e32 v66, v66, v250
	v_sub_f32_e32 v67, v67, v250
	v_sub_f32_e32 v68, v68, v250
	v_sub_f32_e32 v69, v69, v250
	v_sub_f32_e32 v70, v70, v250
	v_sub_f32_e32 v71, v71, v250
	v_sub_f32_e32 v72, v72, v250
	v_sub_f32_e32 v73, v73, v250
	v_sub_f32_e32 v74, v74, v250
	v_sub_f32_e32 v75, v75, v250
	v_sub_f32_e32 v76, v76, v250
	v_sub_f32_e32 v77, v77, v250
	v_sub_f32_e32 v78, v78, v250
	v_sub_f32_e32 v79, v79, v250
	v_sub_f32_e32 v232, v232, v250
	v_sub_f32_e32 v233, v233, v250
	v_sub_f32_e32 v234, v234, v250
	v_sub_f32_e32 v235, v235, v250
	v_sub_f32_e32 v236, v236, v250
	v_sub_f32_e32 v237, v237, v250
	v_sub_f32_e32 v238, v238, v250
	v_sub_f32_e32 v239, v239, v250
	v_sub_f32_e32 v240, v240, v250
	v_sub_f32_e32 v241, v241, v250
	v_sub_f32_e32 v242, v242, v250
	v_sub_f32_e32 v243, v243, v250
	v_sub_f32_e32 v244, v244, v250
	v_sub_f32_e32 v245, v245, v250
	v_sub_f32_e32 v246, v246, v250
	v_sub_f32_e32 v247, v247, v250
	v_exp_f32_e32 v156, v80
	v_exp_f32_e32 v157, v81
	v_exp_f32_e32 v158, v82
	v_exp_f32_e32 v159, v83
	v_exp_f32_e32 v160, v84
	v_exp_f32_e32 v161, v85
	v_exp_f32_e32 v162, v86
	v_exp_f32_e32 v163, v87
	v_exp_f32_e32 v214, v88
	v_exp_f32_e32 v215, v89
	v_exp_f32_e32 v216, v90
	v_exp_f32_e32 v217, v91
	v_exp_f32_e32 v218, v92
	v_exp_f32_e32 v219, v93
	v_exp_f32_e32 v220, v94
	v_exp_f32_e32 v221, v95
	s_nop 0
	v_add_f32_e32 v253, v157, v156
	v_add_f32_e32 v253, v158, v253
	v_add_f32_e32 v253, v159, v253
	v_add_f32_e32 v253, v160, v253
	v_add_f32_e32 v253, v161, v253
	v_add_f32_e32 v253, v162, v253
	v_add_f32_e32 v253, v163, v253
	v_add_f32_e32 v253, v214, v253
	v_add_f32_e32 v253, v215, v253
	v_add_f32_e32 v253, v216, v253
	v_add_f32_e32 v253, v217, v253
	v_add_f32_e32 v253, v218, v253
	v_add_f32_e32 v253, v219, v253
	v_add_f32_e32 v253, v220, v253
	v_add_f32_e32 v190, v221, v253
	v_cvt_pk_bf16_f32 v144, v156, v157
	v_cvt_pk_bf16_f32 v145, v158, v159
	v_cvt_pk_bf16_f32 v146, v160, v161
	v_cvt_pk_bf16_f32 v147, v162, v163
	v_cvt_pk_bf16_f32 v148, v214, v215
	v_cvt_pk_bf16_f32 v149, v216, v217
	v_cvt_pk_bf16_f32 v150, v218, v219
	v_cvt_pk_bf16_f32 v151, v220, v221

.LBB0_174:
	ds_read_b128 v[80:83], v178
	ds_read_b128 v[84:87], v155 offset:4096
	ds_read_b128 v[88:91], v178 offset:8192
	ds_read_b128 v[92:95], v155 offset:12288
	v_add_f32_e32 v192, v190, v192
	s_waitcnt lgkmcnt(8)
	v_mfma_f32_32x32x16_bf16 v[48:63], v[132:135], v[144:147], v[48:63]
	v_exp_f32_e32 v156, v64
	v_exp_f32_e32 v157, v65
	s_waitcnt lgkmcnt(7)
	v_mfma_f32_32x32x16_bf16 v[32:47], v[128:131], v[144:147], v[32:47]
	v_exp_f32_e32 v158, v66
	v_exp_f32_e32 v159, v67
	v_add_f32_e32 v253, v157, v156
	s_waitcnt lgkmcnt(6)
	v_mfma_f32_32x32x16_bf16 v[16:31], v[136:139], v[144:147], v[16:31]
	v_exp_f32_e32 v160, v68
	v_exp_f32_e32 v161, v69
	v_add_f32_e32 v253, v158, v253
	v_add_f32_e32 v253, v159, v253
	s_waitcnt lgkmcnt(5)
	v_mfma_f32_32x32x16_bf16 v[0:15], v[140:143], v[144:147], v[0:15]
	s_add_i32 s7, s84, 0
	s_add_i32 s8, s36, s7
	v_add3_u32 v128, s8, v186, v174
	ds_read_b128 v[144:147], v128 offset:8704
	ds_read_b128 v[198:201], v128 offset:8736
	ds_read_b128 v[224:227], v128 offset:8768
	ds_read_b128 v[228:231], v128 offset:8800
	v_exp_f32_e32 v162, v70
	v_exp_f32_e32 v163, v71
	v_add_f32_e32 v253, v160, v253
	v_add_f32_e32 v253, v161, v253
	s_waitcnt lgkmcnt(7)
	v_mfma_f32_32x32x16_bf16 v[48:63], v[80:83], v[148:151], v[48:63]
	v_add_u32_e32 v190, s7, v188
	v_xor_b32_e32 v191, 64, v190
	ds_read_b128 v[128:131], v190
	ds_read_b128 v[132:135], v191 offset:4096
	ds_read_b128 v[136:139], v190 offset:8192
	ds_read_b128 v[140:143], v191 offset:12288
	v_exp_f32_e32 v214, v72
	v_exp_f32_e32 v215, v73
	v_add_f32_e32 v253, v162, v253
	v_add_f32_e32 v253, v163, v253
	s_waitcnt lgkmcnt(10)
	v_mfma_f32_32x32x16_bf16 v[32:47], v[84:87], v[148:151], v[32:47]
	v_exp_f32_e32 v216, v74
	v_exp_f32_e32 v217, v75
	v_add_f32_e32 v253, v214, v253
	v_add_f32_e32 v253, v215, v253
	s_waitcnt lgkmcnt(9)
	v_mfma_f32_32x32x16_bf16 v[16:31], v[88:91], v[148:151], v[16:31]
	v_exp_f32_e32 v218, v76
	v_exp_f32_e32 v219, v77
	v_add_f32_e32 v253, v216, v253
	v_add_f32_e32 v253, v217, v253
	s_waitcnt lgkmcnt(8)
	v_mfma_f32_32x32x16_bf16 v[0:15], v[92:95], v[148:151], v[0:15]
	v_exp_f32_e32 v220, v78
	v_exp_f32_e32 v221, v79
	v_add_f32_e32 v253, v218, v253
	v_add_f32_e32 v253, v219, v253
	s_waitcnt lgkmcnt(7)
	v_mfma_f32_32x32x16_bf16 v[80:95], v[144:147], v[104:107], v[232:247]
	v_add_f32_e32 v253, v220, v253
	v_cvt_pk_bf16_f32 v148, v214, v215
	v_cvt_pk_bf16_f32 v149, v216, v217
	s_waitcnt lgkmcnt(6)
	v_mfma_f32_32x32x16_bf16 v[80:95], v[198:201], v[96:99], v[80:95]
	v_cvt_pk_bf16_f32 v150, v218, v219
	v_cvt_pk_bf16_f32 v151, v220, v221
	s_waitcnt lgkmcnt(5)
	v_mfma_f32_32x32x16_bf16 v[80:95], v[224:227], v[100:103], v[80:95]
	v_cvt_pk_bf16_f32 v144, v156, v157
	v_cvt_pk_bf16_f32 v145, v158, v159
	s_waitcnt lgkmcnt(4)
	v_mfma_f32_32x32x16_bf16 v[80:95], v[228:231], v[108:111], v[80:95]
	v_add_f32_e32 v193, v221, v253
	v_cvt_pk_bf16_f32 v146, v160, v161
	v_cvt_pk_bf16_f32 v147, v162, v163
	v_cmp_ngt_f32_e32 vcc, s68, v193
	s_cbranch_vccz .LBB0_177
	v_max3_f32 v250, v64, v65, v66
	v_max3_f32 v251, v67, v68, v69
	v_max3_f32 v250, v250, v70, v71
	v_max3_f32 v251, v251, v72, v73
	v_max3_f32 v250, v250, v74, v75
	v_max3_f32 v251, v251, v76, v77
	v_max3_f32 v250, v250, v78, v79
	v_max_f32_e32 v250, v250, v251
	v_mov_b32_e32 v251, v250
	s_nop 1
	v_permlane32_swap_b32_e32 v250, v251
	v_max_f32_e32 v250, v250, v251
	v_cmp_lt_f32_e32 vcc, v154, v250
	s_cbranch_vccz .LBB0_177
	s_nop 1
	v_cndmask_b32_e32 v250, 0, v250, vcc
	v_sub_f32_e32 v251, 0, v250
	v_exp_f32_e32 v251, v251
	s_nop 0
	v_mul_f32_e32 v0, v251, v0
	v_mul_f32_e32 v1, v251, v1
	v_mul_f32_e32 v2, v251, v2
	v_mul_f32_e32 v3, v251, v3
	v_mul_f32_e32 v4, v251, v4
	v_mul_f32_e32 v5, v251, v5
	v_mul_f32_e32 v6, v251, v6
	v_mul_f32_e32 v7, v251, v7
	v_mul_f32_e32 v8, v251, v8
	v_mul_f32_e32 v9, v251, v9
	v_mul_f32_e32 v10, v251, v10
	v_mul_f32_e32 v11, v251, v11
	v_mul_f32_e32 v12, v251, v12
	v_mul_f32_e32 v13, v251, v13
	v_mul_f32_e32 v14, v251, v14
	v_mul_f32_e32 v15, v251, v15
	v_mul_f32_e32 v16, v251, v16
	v_mul_f32_e32 v17, v251, v17
	v_mul_f32_e32 v18, v251, v18
	v_mul_f32_e32 v19, v251, v19
	v_mul_f32_e32 v20, v251, v20
	v_mul_f32_e32 v21, v251, v21
	v_mul_f32_e32 v22, v251, v22
	v_mul_f32_e32 v23, v251, v23
	v_mul_f32_e32 v24, v251, v24
	v_mul_f32_e32 v25, v251, v25
	v_mul_f32_e32 v26, v251, v26
	v_mul_f32_e32 v27, v251, v27
	v_mul_f32_e32 v28, v251, v28
	v_mul_f32_e32 v29, v251, v29
	v_mul_f32_e32 v30, v251, v30
	v_mul_f32_e32 v31, v251, v31
	v_mul_f32_e32 v32, v251, v32
	v_mul_f32_e32 v33, v251, v33
	v_mul_f32_e32 v34, v251, v34
	v_mul_f32_e32 v35, v251, v35
	v_mul_f32_e32 v36, v251, v36
	v_mul_f32_e32 v37, v251, v37
	v_mul_f32_e32 v38, v251, v38
	v_mul_f32_e32 v39, v251, v39
	v_mul_f32_e32 v40, v251, v40
	v_mul_f32_e32 v41, v251, v41
	v_mul_f32_e32 v42, v251, v42
	v_mul_f32_e32 v43, v251, v43
	v_mul_f32_e32 v44, v251, v44
	v_mul_f32_e32 v45, v251, v45
	v_mul_f32_e32 v46, v251, v46
	v_mul_f32_e32 v47, v251, v47
	v_mul_f32_e32 v48, v251, v48
	v_mul_f32_e32 v49, v251, v49
	v_mul_f32_e32 v50, v251, v50
	v_mul_f32_e32 v51, v251, v51
	v_mul_f32_e32 v52, v251, v52
	v_mul_f32_e32 v53, v251, v53
	v_mul_f32_e32 v54, v251, v54
	v_mul_f32_e32 v55, v251, v55
	v_mul_f32_e32 v56, v251, v56
	v_mul_f32_e32 v57, v251, v57
	v_mul_f32_e32 v58, v251, v58
	v_mul_f32_e32 v59, v251, v59
	v_mul_f32_e32 v60, v251, v60
	v_mul_f32_e32 v61, v251, v61
	v_mul_f32_e32 v62, v251, v62
	v_mul_f32_e32 v63, v251, v63
	v_mul_f32_e32 v192, v251, v192
	v_sub_f32_e32 v64, v64, v250
	v_sub_f32_e32 v65, v65, v250
	v_sub_f32_e32 v66, v66, v250
	v_sub_f32_e32 v67, v67, v250
	v_sub_f32_e32 v68, v68, v250
	v_sub_f32_e32 v69, v69, v250
	v_sub_f32_e32 v70, v70, v250
	v_sub_f32_e32 v71, v71, v250
	v_sub_f32_e32 v72, v72, v250
	v_sub_f32_e32 v73, v73, v250
	v_sub_f32_e32 v74, v74, v250
	v_sub_f32_e32 v75, v75, v250
	v_sub_f32_e32 v76, v76, v250
	v_sub_f32_e32 v77, v77, v250
	v_sub_f32_e32 v78, v78, v250
	v_sub_f32_e32 v79, v79, v250
	v_sub_f32_e32 v80, v80, v250
	v_sub_f32_e32 v81, v81, v250
	v_sub_f32_e32 v82, v82, v250
	v_sub_f32_e32 v83, v83, v250
	v_sub_f32_e32 v84, v84, v250
	v_sub_f32_e32 v85, v85, v250
	v_sub_f32_e32 v86, v86, v250
	v_sub_f32_e32 v87, v87, v250
	v_sub_f32_e32 v88, v88, v250
	v_sub_f32_e32 v89, v89, v250
	v_sub_f32_e32 v90, v90, v250
	v_sub_f32_e32 v91, v91, v250
	v_sub_f32_e32 v92, v92, v250
	v_sub_f32_e32 v93, v93, v250
	v_sub_f32_e32 v94, v94, v250
	v_sub_f32_e32 v95, v95, v250
	v_sub_f32_e32 v232, v232, v250
	v_sub_f32_e32 v233, v233, v250
	v_sub_f32_e32 v234, v234, v250
	v_sub_f32_e32 v235, v235, v250
	v_sub_f32_e32 v236, v236, v250
	v_sub_f32_e32 v237, v237, v250
	v_sub_f32_e32 v238, v238, v250
	v_sub_f32_e32 v239, v239, v250
	v_sub_f32_e32 v240, v240, v250
	v_sub_f32_e32 v241, v241, v250
	v_sub_f32_e32 v242, v242, v250
	v_sub_f32_e32 v243, v243, v250
	v_sub_f32_e32 v244, v244, v250
	v_sub_f32_e32 v245, v245, v250
	v_sub_f32_e32 v246, v246, v250
	v_sub_f32_e32 v247, v247, v250
	v_exp_f32_e32 v156, v64
	v_exp_f32_e32 v157, v65
	v_exp_f32_e32 v158, v66
	v_exp_f32_e32 v159, v67
	v_exp_f32_e32 v160, v68
	v_exp_f32_e32 v161, v69
	v_exp_f32_e32 v162, v70
	v_exp_f32_e32 v163, v71
	v_exp_f32_e32 v214, v72
	v_exp_f32_e32 v215, v73
	v_exp_f32_e32 v216, v74
	v_exp_f32_e32 v217, v75
	v_exp_f32_e32 v218, v76
	v_exp_f32_e32 v219, v77
	v_exp_f32_e32 v220, v78
	v_exp_f32_e32 v221, v79
	s_nop 0
	v_add_f32_e32 v253, v157, v156
	v_add_f32_e32 v253, v158, v253
	v_add_f32_e32 v253, v159, v253
	v_add_f32_e32 v253, v160, v253
	v_add_f32_e32 v253, v161, v253
	v_add_f32_e32 v253, v162, v253
	v_add_f32_e32 v253, v163, v253
	v_add_f32_e32 v253, v214, v253
	v_add_f32_e32 v253, v215, v253
	v_add_f32_e32 v253, v216, v253
	v_add_f32_e32 v253, v217, v253
	v_add_f32_e32 v253, v218, v253
	v_add_f32_e32 v253, v219, v253
	v_add_f32_e32 v253, v220, v253
	v_add_f32_e32 v193, v221, v253
	v_cvt_pk_bf16_f32 v144, v156, v157
	v_cvt_pk_bf16_f32 v145, v158, v159
	v_cvt_pk_bf16_f32 v146, v160, v161
	v_cvt_pk_bf16_f32 v147, v162, v163
	v_cvt_pk_bf16_f32 v148, v214, v215
	v_cvt_pk_bf16_f32 v149, v216, v217
	v_cvt_pk_bf16_f32 v150, v218, v219
	v_cvt_pk_bf16_f32 v151, v220, v221

.LBB0_179:
	v_xor_b32_e32 v72, 32, v190
	v_xor_b32_e32 v76, 0x60, v190
	ds_read_b128 v[64:67], v72
	ds_read_b128 v[68:71], v76 offset:4096
	ds_read_b128 v[72:75], v72 offset:8192
	ds_read_b128 v[76:79], v76 offset:12288
	v_add_f32_e32 v155, v193, v192
	v_mfma_f32_32x32x16_bf16 v[48:63], v[128:131], v[144:147], v[48:63]
	v_exp_f32_e32 v156, v80
	v_exp_f32_e32 v157, v81
	v_mfma_f32_32x32x16_bf16 v[32:47], v[132:135], v[144:147], v[32:47]
	v_exp_f32_e32 v158, v82
	v_exp_f32_e32 v159, v83
	v_add_f32_e32 v253, v157, v156
	v_mfma_f32_32x32x16_bf16 v[16:31], v[136:139], v[144:147], v[16:31]
	v_exp_f32_e32 v160, v84
	v_exp_f32_e32 v161, v85
	v_add_f32_e32 v253, v158, v253
	v_add_f32_e32 v253, v159, v253
	v_mfma_f32_32x32x16_bf16 v[0:15], v[140:143], v[144:147], v[0:15]
	v_add_u32_e32 v128, s83, v187
	ds_read_b128 v[144:147], v128
	ds_read_b128 v[192:195], v128 offset:32
	ds_read_b128 v[198:201], v128 offset:64
	ds_read_b128 v[224:227], v128 offset:96
	v_exp_f32_e32 v162, v86
	v_exp_f32_e32 v163, v87
	v_add_f32_e32 v253, v160, v253
	v_add_f32_e32 v253, v161, v253
	s_waitcnt lgkmcnt(7)
	v_mfma_f32_32x32x16_bf16 v[48:63], v[64:67], v[148:151], v[48:63]
	ds_read_b128 v[140:143], v191
	ds_read_b128 v[136:139], v190 offset:4096
	ds_read_b128 v[132:135], v191 offset:8192
	ds_read_b128 v[128:131], v190 offset:12288
	v_exp_f32_e32 v214, v88
	v_exp_f32_e32 v215, v89
	v_add_f32_e32 v253, v162, v253
	v_add_f32_e32 v253, v163, v253
	s_waitcnt lgkmcnt(10)
	v_mfma_f32_32x32x16_bf16 v[32:47], v[68:71], v[148:151], v[32:47]
	v_exp_f32_e32 v216, v90
	v_exp_f32_e32 v217, v91
	v_add_f32_e32 v253, v214, v253
	v_add_f32_e32 v253, v215, v253
	s_waitcnt lgkmcnt(9)
	v_mfma_f32_32x32x16_bf16 v[16:31], v[72:75], v[148:151], v[16:31]
	v_exp_f32_e32 v218, v92
	v_exp_f32_e32 v219, v93
	v_add_f32_e32 v253, v216, v253
	v_add_f32_e32 v253, v217, v253
	s_waitcnt lgkmcnt(8)
	v_mfma_f32_32x32x16_bf16 v[0:15], v[76:79], v[148:151], v[0:15]
	v_exp_f32_e32 v220, v94
	v_exp_f32_e32 v221, v95
	v_add_f32_e32 v253, v218, v253
	v_add_f32_e32 v253, v219, v253
	s_waitcnt lgkmcnt(7)
	v_mfma_f32_32x32x16_bf16 v[64:79], v[144:147], v[104:107], v[232:247]
	v_add_f32_e32 v253, v220, v253
	v_cvt_pk_bf16_f32 v148, v156, v157
	v_cvt_pk_bf16_f32 v149, v158, v159
	s_waitcnt lgkmcnt(6)
	v_mfma_f32_32x32x16_bf16 v[64:79], v[192:195], v[96:99], v[64:79]
	v_cvt_pk_bf16_f32 v150, v160, v161
	v_cvt_pk_bf16_f32 v151, v162, v163
	s_waitcnt lgkmcnt(5)
	v_mfma_f32_32x32x16_bf16 v[64:79], v[198:201], v[100:103], v[64:79]
	v_cvt_pk_bf16_f32 v144, v214, v215
	v_cvt_pk_bf16_f32 v145, v216, v217
	s_waitcnt lgkmcnt(4)
	v_mfma_f32_32x32x16_bf16 v[64:79], v[224:227], v[108:111], v[64:79]
	v_add_f32_e32 v178, v221, v253
	v_cvt_pk_bf16_f32 v146, v218, v219
	v_cvt_pk_bf16_f32 v147, v220, v221
	v_cmp_ngt_f32_e32 vcc, s68, v178
	s_cbranch_vccz .LBB0_182
	v_max3_f32 v250, v80, v81, v82
	v_max3_f32 v251, v83, v84, v85
	v_max3_f32 v250, v250, v86, v87
	v_max3_f32 v251, v251, v88, v89
	v_max3_f32 v250, v250, v90, v91
	v_max3_f32 v251, v251, v92, v93
	v_max3_f32 v250, v250, v94, v95
	v_max_f32_e32 v250, v250, v251
	v_mov_b32_e32 v251, v250
	s_nop 1
	v_permlane32_swap_b32_e32 v250, v251
	v_max_f32_e32 v250, v250, v251
	v_cmp_lt_f32_e32 vcc, v154, v250
	s_cbranch_vccz .LBB0_182
	s_nop 1
	v_cndmask_b32_e32 v250, 0, v250, vcc
	v_sub_f32_e32 v251, 0, v250
	v_exp_f32_e32 v251, v251
	s_nop 0
	v_mul_f32_e32 v0, v251, v0
	v_mul_f32_e32 v1, v251, v1
	v_mul_f32_e32 v2, v251, v2
	v_mul_f32_e32 v3, v251, v3
	v_mul_f32_e32 v4, v251, v4
	v_mul_f32_e32 v5, v251, v5
	v_mul_f32_e32 v6, v251, v6
	v_mul_f32_e32 v7, v251, v7
	v_mul_f32_e32 v8, v251, v8
	v_mul_f32_e32 v9, v251, v9
	v_mul_f32_e32 v10, v251, v10
	v_mul_f32_e32 v11, v251, v11
	v_mul_f32_e32 v12, v251, v12
	v_mul_f32_e32 v13, v251, v13
	v_mul_f32_e32 v14, v251, v14
	v_mul_f32_e32 v15, v251, v15
	v_mul_f32_e32 v16, v251, v16
	v_mul_f32_e32 v17, v251, v17
	v_mul_f32_e32 v18, v251, v18
	v_mul_f32_e32 v19, v251, v19
	v_mul_f32_e32 v20, v251, v20
	v_mul_f32_e32 v21, v251, v21
	v_mul_f32_e32 v22, v251, v22
	v_mul_f32_e32 v23, v251, v23
	v_mul_f32_e32 v24, v251, v24
	v_mul_f32_e32 v25, v251, v25
	v_mul_f32_e32 v26, v251, v26
	v_mul_f32_e32 v27, v251, v27
	v_mul_f32_e32 v28, v251, v28
	v_mul_f32_e32 v29, v251, v29
	v_mul_f32_e32 v30, v251, v30
	v_mul_f32_e32 v31, v251, v31
	v_mul_f32_e32 v32, v251, v32
	v_mul_f32_e32 v33, v251, v33
	v_mul_f32_e32 v34, v251, v34
	v_mul_f32_e32 v35, v251, v35
	v_mul_f32_e32 v36, v251, v36
	v_mul_f32_e32 v37, v251, v37
	v_mul_f32_e32 v38, v251, v38
	v_mul_f32_e32 v39, v251, v39
	v_mul_f32_e32 v40, v251, v40
	v_mul_f32_e32 v41, v251, v41
	v_mul_f32_e32 v42, v251, v42
	v_mul_f32_e32 v43, v251, v43
	v_mul_f32_e32 v44, v251, v44
	v_mul_f32_e32 v45, v251, v45
	v_mul_f32_e32 v46, v251, v46
	v_mul_f32_e32 v47, v251, v47
	v_mul_f32_e32 v48, v251, v48
	v_mul_f32_e32 v49, v251, v49
	v_mul_f32_e32 v50, v251, v50
	v_mul_f32_e32 v51, v251, v51
	v_mul_f32_e32 v52, v251, v52
	v_mul_f32_e32 v53, v251, v53
	v_mul_f32_e32 v54, v251, v54
	v_mul_f32_e32 v55, v251, v55
	v_mul_f32_e32 v56, v251, v56
	v_mul_f32_e32 v57, v251, v57
	v_mul_f32_e32 v58, v251, v58
	v_mul_f32_e32 v59, v251, v59
	v_mul_f32_e32 v60, v251, v60
	v_mul_f32_e32 v61, v251, v61
	v_mul_f32_e32 v62, v251, v62
	v_mul_f32_e32 v63, v251, v63
	v_mul_f32_e32 v155, v251, v155
	v_sub_f32_e32 v80, v80, v250
	v_sub_f32_e32 v81, v81, v250
	v_sub_f32_e32 v82, v82, v250
	v_sub_f32_e32 v83, v83, v250
	v_sub_f32_e32 v84, v84, v250
	v_sub_f32_e32 v85, v85, v250
	v_sub_f32_e32 v86, v86, v250
	v_sub_f32_e32 v87, v87, v250
	v_sub_f32_e32 v88, v88, v250
	v_sub_f32_e32 v89, v89, v250
	v_sub_f32_e32 v90, v90, v250
	v_sub_f32_e32 v91, v91, v250
	v_sub_f32_e32 v92, v92, v250
	v_sub_f32_e32 v93, v93, v250
	v_sub_f32_e32 v94, v94, v250
	v_sub_f32_e32 v95, v95, v250
	v_sub_f32_e32 v64, v64, v250
	v_sub_f32_e32 v65, v65, v250
	v_sub_f32_e32 v66, v66, v250
	v_sub_f32_e32 v67, v67, v250
	v_sub_f32_e32 v68, v68, v250
	v_sub_f32_e32 v69, v69, v250
	v_sub_f32_e32 v70, v70, v250
	v_sub_f32_e32 v71, v71, v250
	v_sub_f32_e32 v72, v72, v250
	v_sub_f32_e32 v73, v73, v250
	v_sub_f32_e32 v74, v74, v250
	v_sub_f32_e32 v75, v75, v250
	v_sub_f32_e32 v76, v76, v250
	v_sub_f32_e32 v77, v77, v250
	v_sub_f32_e32 v78, v78, v250
	v_sub_f32_e32 v79, v79, v250
	v_sub_f32_e32 v232, v232, v250
	v_sub_f32_e32 v233, v233, v250
	v_sub_f32_e32 v234, v234, v250
	v_sub_f32_e32 v235, v235, v250
	v_sub_f32_e32 v236, v236, v250
	v_sub_f32_e32 v237, v237, v250
	v_sub_f32_e32 v238, v238, v250
	v_sub_f32_e32 v239, v239, v250
	v_sub_f32_e32 v240, v240, v250
	v_sub_f32_e32 v241, v241, v250
	v_sub_f32_e32 v242, v242, v250
	v_sub_f32_e32 v243, v243, v250
	v_sub_f32_e32 v244, v244, v250
	v_sub_f32_e32 v245, v245, v250
	v_sub_f32_e32 v246, v246, v250
	v_sub_f32_e32 v247, v247, v250
	v_exp_f32_e32 v156, v80
	v_exp_f32_e32 v157, v81
	v_exp_f32_e32 v158, v82
	v_exp_f32_e32 v159, v83
	v_exp_f32_e32 v160, v84
	v_exp_f32_e32 v161, v85
	v_exp_f32_e32 v162, v86
	v_exp_f32_e32 v163, v87
	v_exp_f32_e32 v214, v88
	v_exp_f32_e32 v215, v89
	v_exp_f32_e32 v216, v90
	v_exp_f32_e32 v217, v91
	v_exp_f32_e32 v218, v92
	v_exp_f32_e32 v219, v93
	v_exp_f32_e32 v220, v94
	v_exp_f32_e32 v221, v95
	s_nop 0
	v_add_f32_e32 v253, v157, v156
	v_add_f32_e32 v253, v158, v253
	v_add_f32_e32 v253, v159, v253
	v_add_f32_e32 v253, v160, v253
	v_add_f32_e32 v253, v161, v253
	v_add_f32_e32 v253, v162, v253
	v_add_f32_e32 v253, v163, v253
	v_add_f32_e32 v253, v214, v253
	v_add_f32_e32 v253, v215, v253
	v_add_f32_e32 v253, v216, v253
	v_add_f32_e32 v253, v217, v253
	v_add_f32_e32 v253, v218, v253
	v_add_f32_e32 v253, v219, v253
	v_add_f32_e32 v253, v220, v253
	v_add_f32_e32 v178, v221, v253
	v_cvt_pk_bf16_f32 v148, v156, v157
	v_cvt_pk_bf16_f32 v149, v158, v159
	v_cvt_pk_bf16_f32 v150, v160, v161
	v_cvt_pk_bf16_f32 v151, v162, v163
	v_cvt_pk_bf16_f32 v144, v214, v215
	v_cvt_pk_bf16_f32 v145, v216, v217
	v_cvt_pk_bf16_f32 v146, v218, v219
	v_cvt_pk_bf16_f32 v147, v220, v221
